# causal-mask block in the 4 band-loop sites compacted: per-lane difference computed once, inline-constant compares into 4 rotating SGPR mask pairs, no index adds or hazard nops (127 -> 66 instructions)
# baseline (speedup 1.0000x reference)
.LBB0_425:
	s_add_i32 s16, s92, s50
	s_add_i32 s8, s90, s87
	s_add_i32 s9, s16, 2
	s_cmp_lt_i32 s9, 0
	s_mov_b32 s9, m0
	s_mov_b32 m0, s8
	s_nop 0
	global_load_lds_dwordx4 v[206:207], off
	s_mov_b32 m0, s9
	s_cbranch_scc1 .LBB0_427
	s_add_i32 s94, s16, 3
	s_lshl_b32 s94, s94, 1
	s_cmp_ge_u32 s84, s94
	s_cbranch_scc1 .LBB0_427
	v_sub_u32_e32 v253, v219, v0
	v_add_u32_e32 v253, 0x7b, v253
	v_cmp_ge_i32_e64 s[94:95], v253, 32
	v_cmp_ge_i32_e64 s[96:97], v253, 1
	v_cmp_ge_i32_e64 s[98:99], v253, 0
	v_cndmask_b32_e64 v98, v236, v98, s[94:95]
	v_cmp_ge_i32_e64 s[100:101], v253, 33
	v_cndmask_b32_e64 v115, v236, v115, s[96:97]
	v_cmp_ge_i32_e64 s[94:95], v253, 2
	v_cndmask_b32_e64 v114, v236, v114, s[98:99]
	v_cmp_ge_i32_e64 s[96:97], v253, 34
	v_cndmask_b32_e64 v99, v236, v99, s[100:101]
	v_cmp_ge_i32_e64 s[98:99], v253, 3
	v_cndmask_b32_e64 v116, v236, v116, s[94:95]
	v_cmp_ge_i32_e64 s[100:101], v253, 35
	v_cndmask_b32_e64 v100, v236, v100, s[96:97]
	v_cmp_ge_i32_e64 s[94:95], v253, 8
	v_cndmask_b32_e64 v117, v236, v117, s[98:99]
	v_cmp_ge_i32_e64 s[96:97], v253, 40
	v_cndmask_b32_e64 v101, v236, v101, s[100:101]
	v_cmp_ge_i32_e64 s[98:99], v253, 9
	v_cndmask_b32_e64 v118, v236, v118, s[94:95]
	v_cmp_ge_i32_e64 s[100:101], v253, 41
	v_cndmask_b32_e64 v102, v236, v102, s[96:97]
	v_cmp_ge_i32_e64 s[94:95], v253, 10
	v_cndmask_b32_e64 v119, v236, v119, s[98:99]
	v_cmp_ge_i32_e64 s[96:97], v253, 42
	v_cndmask_b32_e64 v103, v236, v103, s[100:101]
	v_cmp_ge_i32_e64 s[98:99], v253, 11
	v_cndmask_b32_e64 v120, v236, v120, s[94:95]
	v_cmp_ge_i32_e64 s[100:101], v253, 43
	v_cndmask_b32_e64 v104, v236, v104, s[96:97]
	v_cmp_ge_i32_e64 s[94:95], v253, 16
	v_cndmask_b32_e64 v121, v236, v121, s[98:99]
	v_cmp_ge_i32_e64 s[96:97], v253, 48
	v_cndmask_b32_e64 v105, v236, v105, s[100:101]
	v_cmp_ge_i32_e64 s[98:99], v253, 17
	v_cndmask_b32_e64 v122, v236, v122, s[94:95]
	v_cmp_ge_i32_e64 s[100:101], v253, 49
	v_cndmask_b32_e64 v106, v236, v106, s[96:97]
	v_cmp_ge_i32_e64 s[94:95], v253, 18
	v_cndmask_b32_e64 v123, v236, v123, s[98:99]
	v_cmp_ge_i32_e64 s[96:97], v253, 50
	v_cndmask_b32_e64 v107, v236, v107, s[100:101]
	v_cmp_ge_i32_e64 s[98:99], v253, 19
	v_cndmask_b32_e64 v124, v236, v124, s[94:95]
	v_cmp_ge_i32_e64 s[100:101], v253, 51
	v_cndmask_b32_e64 v108, v236, v108, s[96:97]
	v_cmp_ge_i32_e64 s[94:95], v253, 24
	v_cndmask_b32_e64 v125, v236, v125, s[98:99]
	v_cmp_ge_i32_e64 s[96:97], v253, 56
	v_cndmask_b32_e64 v109, v236, v109, s[100:101]
	v_cmp_ge_i32_e64 s[98:99], v253, 25
	v_cndmask_b32_e64 v126, v236, v126, s[94:95]
	v_cmp_ge_i32_e64 s[100:101], v253, 57
	v_cndmask_b32_e64 v110, v236, v110, s[96:97]
	v_cmp_ge_i32_e64 s[94:95], v253, 26
	v_cndmask_b32_e64 v127, v236, v127, s[98:99]
	v_cmp_ge_i32_e64 s[96:97], v253, 58
	v_cndmask_b32_e64 v111, v236, v111, s[100:101]
	v_cmp_ge_i32_e64 s[98:99], v253, 27
	v_cndmask_b32_e64 v128, v236, v128, s[94:95]
	v_cmp_ge_i32_e64 s[100:101], v253, 59
	v_cndmask_b32_e64 v112, v236, v112, s[96:97]
	v_cndmask_b32_e64 v129, v236, v129, s[98:99]
	v_cndmask_b32_e64 v113, v236, v113, s[100:101]

.LBB0_442:
	s_add_i32 s16, s16, 3
	s_cmp_lt_i32 s16, 0
	s_cbranch_scc1 .LBB0_444
	s_add_i32 s94, s16, 1
	s_lshl_b32 s94, s94, 1
	s_cmp_ge_u32 s84, s94
	s_cbranch_scc1 .LBB0_444
	v_sub_u32_e32 v253, v219, v0
	v_add_u32_e32 v253, 59, v253
	v_cmp_ge_i32_e64 s[94:95], v253, 32
	v_cmp_ge_i32_e64 s[96:97], v253, 1
	v_cmp_ge_i32_e64 s[98:99], v253, 0
	v_cndmask_b32_e64 v50, v236, v50, s[94:95]
	v_cmp_ge_i32_e64 s[100:101], v253, 33
	v_cndmask_b32_e64 v83, v236, v83, s[96:97]
	v_cmp_ge_i32_e64 s[94:95], v253, 2
	v_cndmask_b32_e64 v82, v236, v82, s[98:99]
	v_cmp_ge_i32_e64 s[96:97], v253, 34
	v_cndmask_b32_e64 v51, v236, v51, s[100:101]
	v_cmp_ge_i32_e64 s[98:99], v253, 3
	v_cndmask_b32_e64 v84, v236, v84, s[94:95]
	v_cmp_ge_i32_e64 s[100:101], v253, 35
	v_cndmask_b32_e64 v52, v236, v52, s[96:97]
	v_cmp_ge_i32_e64 s[94:95], v253, 8
	v_cndmask_b32_e64 v85, v236, v85, s[98:99]
	v_cmp_ge_i32_e64 s[96:97], v253, 40
	v_cndmask_b32_e64 v53, v236, v53, s[100:101]
	v_cmp_ge_i32_e64 s[98:99], v253, 9
	v_cndmask_b32_e64 v86, v236, v86, s[94:95]
	v_cmp_ge_i32_e64 s[100:101], v253, 41
	v_cndmask_b32_e64 v54, v236, v54, s[96:97]
	v_cmp_ge_i32_e64 s[94:95], v253, 10
	v_cndmask_b32_e64 v87, v236, v87, s[98:99]
	v_cmp_ge_i32_e64 s[96:97], v253, 42
	v_cndmask_b32_e64 v55, v236, v55, s[100:101]
	v_cmp_ge_i32_e64 s[98:99], v253, 11
	v_cndmask_b32_e64 v88, v236, v88, s[94:95]
	v_cmp_ge_i32_e64 s[100:101], v253, 43
	v_cndmask_b32_e64 v56, v236, v56, s[96:97]
	v_cmp_ge_i32_e64 s[94:95], v253, 16
	v_cndmask_b32_e64 v89, v236, v89, s[98:99]
	v_cmp_ge_i32_e64 s[96:97], v253, 48
	v_cndmask_b32_e64 v57, v236, v57, s[100:101]
	v_cmp_ge_i32_e64 s[98:99], v253, 17
	v_cndmask_b32_e64 v90, v236, v90, s[94:95]
	v_cmp_ge_i32_e64 s[100:101], v253, 49
	v_cndmask_b32_e64 v58, v236, v58, s[96:97]
	v_cmp_ge_i32_e64 s[94:95], v253, 18
	v_cndmask_b32_e64 v91, v236, v91, s[98:99]
	v_cmp_ge_i32_e64 s[96:97], v253, 50
	v_cndmask_b32_e64 v59, v236, v59, s[100:101]
	v_cmp_ge_i32_e64 s[98:99], v253, 19
	v_cndmask_b32_e64 v92, v236, v92, s[94:95]
	v_cmp_ge_i32_e64 s[100:101], v253, 51
	v_cndmask_b32_e64 v60, v236, v60, s[96:97]
	v_cmp_ge_i32_e64 s[94:95], v253, 24
	v_cndmask_b32_e64 v93, v236, v93, s[98:99]
	v_cmp_ge_i32_e64 s[96:97], v253, 56
	v_cndmask_b32_e64 v61, v236, v61, s[100:101]
	v_cmp_ge_i32_e64 s[98:99], v253, 25
	v_cndmask_b32_e64 v94, v236, v94, s[94:95]
	v_cmp_ge_i32_e64 s[100:101], v253, 57
	v_cndmask_b32_e64 v62, v236, v62, s[96:97]
	v_cmp_ge_i32_e64 s[94:95], v253, 26
	v_cndmask_b32_e64 v95, v236, v95, s[98:99]
	v_cmp_ge_i32_e64 s[96:97], v253, 58
	v_cndmask_b32_e64 v63, v236, v63, s[100:101]
	v_cmp_ge_i32_e64 s[98:99], v253, 27
	v_cndmask_b32_e64 v96, v236, v96, s[94:95]
	v_cmp_ge_i32_e64 s[100:101], v253, 59
	v_cndmask_b32_e64 v64, v236, v64, s[96:97]
	v_cndmask_b32_e64 v97, v236, v97, s[98:99]
	v_cndmask_b32_e64 v65, v236, v65, s[100:101]

.LBB0_503:
	v_lshl_add_u64 v[14:15], v[226:227], 0, s[40:41]
	v_lshl_add_u64 v[98:99], v[14:15], 0, s[18:19]
	s_add_i32 s8, s87, s83
	s_mov_b32 s9, m0
	s_mov_b32 m0, s8
	s_nop 0
	global_load_lds_dwordx4 v[98:99], off
	s_mov_b32 m0, s9
	s_add_i32 s16, s89, s46
	v_lshl_add_u64 v[232:233], v[228:229], 0, s[40:41]
	s_add_i32 s8, s87, s84
	s_add_i32 s9, s16, 2
	v_lshl_add_u64 v[98:99], v[232:233], 0, s[18:19]
	s_cmp_lt_i32 s9, 0
	s_mov_b32 s9, m0
	s_mov_b32 m0, s8
	s_nop 0
	global_load_lds_dwordx4 v[98:99], off
	s_mov_b32 m0, s9
	s_cbranch_scc1 .LBB0_505
	s_add_i32 s94, s16, 3
	s_lshl_b32 s94, s94, 1
	s_cmp_ge_u32 s50, s94
	s_cbranch_scc1 .LBB0_505
	v_sub_u32_e32 v253, v246, v0
	v_add_u32_e32 v253, 0x7b, v253
	v_cmp_ge_i32_e64 s[94:95], v253, 32
	v_cmp_ge_i32_e64 s[96:97], v253, 1
	v_cmp_ge_i32_e64 s[98:99], v253, 0
	v_cndmask_b32_e64 v128, v236, v128, s[94:95]
	v_cmp_ge_i32_e64 s[100:101], v253, 33
	v_cndmask_b32_e64 v145, v236, v145, s[96:97]
	v_cmp_ge_i32_e64 s[94:95], v253, 2
	v_cndmask_b32_e64 v144, v236, v144, s[98:99]
	v_cmp_ge_i32_e64 s[96:97], v253, 34
	v_cndmask_b32_e64 v129, v236, v129, s[100:101]
	v_cmp_ge_i32_e64 s[98:99], v253, 3
	v_cndmask_b32_e64 v146, v236, v146, s[94:95]
	v_cmp_ge_i32_e64 s[100:101], v253, 35
	v_cndmask_b32_e64 v130, v236, v130, s[96:97]
	v_cmp_ge_i32_e64 s[94:95], v253, 8
	v_cndmask_b32_e64 v147, v236, v147, s[98:99]
	v_cmp_ge_i32_e64 s[96:97], v253, 40
	v_cndmask_b32_e64 v131, v236, v131, s[100:101]
	v_cmp_ge_i32_e64 s[98:99], v253, 9
	v_cndmask_b32_e64 v148, v236, v148, s[94:95]
	v_cmp_ge_i32_e64 s[100:101], v253, 41
	v_cndmask_b32_e64 v132, v236, v132, s[96:97]
	v_cmp_ge_i32_e64 s[94:95], v253, 10
	v_cndmask_b32_e64 v149, v236, v149, s[98:99]
	v_cmp_ge_i32_e64 s[96:97], v253, 42
	v_cndmask_b32_e64 v133, v236, v133, s[100:101]
	v_cmp_ge_i32_e64 s[98:99], v253, 11
	v_cndmask_b32_e64 v150, v236, v150, s[94:95]
	v_cmp_ge_i32_e64 s[100:101], v253, 43
	v_cndmask_b32_e64 v134, v236, v134, s[96:97]
	v_cmp_ge_i32_e64 s[94:95], v253, 16
	v_cndmask_b32_e64 v151, v236, v151, s[98:99]
	v_cmp_ge_i32_e64 s[96:97], v253, 48
	v_cndmask_b32_e64 v135, v236, v135, s[100:101]
	v_cmp_ge_i32_e64 s[98:99], v253, 17
	v_cndmask_b32_e64 v152, v236, v152, s[94:95]
	v_cmp_ge_i32_e64 s[100:101], v253, 49
	v_cndmask_b32_e64 v136, v236, v136, s[96:97]
	v_cmp_ge_i32_e64 s[94:95], v253, 18
	v_cndmask_b32_e64 v153, v236, v153, s[98:99]
	v_cmp_ge_i32_e64 s[96:97], v253, 50
	v_cndmask_b32_e64 v137, v236, v137, s[100:101]
	v_cmp_ge_i32_e64 s[98:99], v253, 19
	v_cndmask_b32_e64 v154, v236, v154, s[94:95]
	v_cmp_ge_i32_e64 s[100:101], v253, 51
	v_cndmask_b32_e64 v138, v236, v138, s[96:97]
	v_cmp_ge_i32_e64 s[94:95], v253, 24
	v_cndmask_b32_e64 v155, v236, v155, s[98:99]
	v_cmp_ge_i32_e64 s[96:97], v253, 56
	v_cndmask_b32_e64 v139, v236, v139, s[100:101]
	v_cmp_ge_i32_e64 s[98:99], v253, 25
	v_cndmask_b32_e64 v156, v236, v156, s[94:95]
	v_cmp_ge_i32_e64 s[100:101], v253, 57
	v_cndmask_b32_e64 v140, v236, v140, s[96:97]
	v_cmp_ge_i32_e64 s[94:95], v253, 26
	v_cndmask_b32_e64 v157, v236, v157, s[98:99]
	v_cmp_ge_i32_e64 s[96:97], v253, 58
	v_cndmask_b32_e64 v141, v236, v141, s[100:101]
	v_cmp_ge_i32_e64 s[98:99], v253, 27
	v_cndmask_b32_e64 v158, v236, v158, s[94:95]
	v_cmp_ge_i32_e64 s[100:101], v253, 59
	v_cndmask_b32_e64 v142, v236, v142, s[96:97]
	v_cndmask_b32_e64 v159, v236, v159, s[98:99]
	v_cndmask_b32_e64 v143, v236, v143, s[100:101]

.LBB0_518:
	s_add_i32 s16, s16, 3
	s_cmp_lt_i32 s16, 0
	s_cbranch_scc1 .LBB0_520
	s_add_i32 s94, s16, 1
	s_lshl_b32 s94, s94, 1
	s_cmp_ge_u32 s50, s94
	s_cbranch_scc1 .LBB0_520
	v_sub_u32_e32 v253, v246, v0
	v_add_u32_e32 v253, 59, v253
	v_cmp_ge_i32_e64 s[94:95], v253, 32
	v_cmp_ge_i32_e64 s[96:97], v253, 1
	v_cmp_ge_i32_e64 s[98:99], v253, 0
	v_cndmask_b32_e64 v96, v236, v96, s[94:95]
	v_cmp_ge_i32_e64 s[100:101], v253, 33
	v_cndmask_b32_e64 v113, v236, v113, s[96:97]
	v_cmp_ge_i32_e64 s[94:95], v253, 2
	v_cndmask_b32_e64 v112, v236, v112, s[98:99]
	v_cmp_ge_i32_e64 s[96:97], v253, 34
	v_cndmask_b32_e64 v97, v236, v97, s[100:101]
	v_cmp_ge_i32_e64 s[98:99], v253, 3
	v_cndmask_b32_e64 v114, v236, v114, s[94:95]
	v_cmp_ge_i32_e64 s[100:101], v253, 35
	v_cndmask_b32_e64 v98, v236, v98, s[96:97]
	v_cmp_ge_i32_e64 s[94:95], v253, 8
	v_cndmask_b32_e64 v115, v236, v115, s[98:99]
	v_cmp_ge_i32_e64 s[96:97], v253, 40
	v_cndmask_b32_e64 v99, v236, v99, s[100:101]
	v_cmp_ge_i32_e64 s[98:99], v253, 9
	v_cndmask_b32_e64 v116, v236, v116, s[94:95]
	v_cmp_ge_i32_e64 s[100:101], v253, 41
	v_cndmask_b32_e64 v100, v236, v100, s[96:97]
	v_cmp_ge_i32_e64 s[94:95], v253, 10
	v_cndmask_b32_e64 v117, v236, v117, s[98:99]
	v_cmp_ge_i32_e64 s[96:97], v253, 42
	v_cndmask_b32_e64 v101, v236, v101, s[100:101]
	v_cmp_ge_i32_e64 s[98:99], v253, 11
	v_cndmask_b32_e64 v118, v236, v118, s[94:95]
	v_cmp_ge_i32_e64 s[100:101], v253, 43
	v_cndmask_b32_e64 v102, v236, v102, s[96:97]
	v_cmp_ge_i32_e64 s[94:95], v253, 16
	v_cndmask_b32_e64 v119, v236, v119, s[98:99]
	v_cmp_ge_i32_e64 s[96:97], v253, 48
	v_cndmask_b32_e64 v103, v236, v103, s[100:101]
	v_cmp_ge_i32_e64 s[98:99], v253, 17
	v_cndmask_b32_e64 v120, v236, v120, s[94:95]
	v_cmp_ge_i32_e64 s[100:101], v253, 49
	v_cndmask_b32_e64 v104, v236, v104, s[96:97]
	v_cmp_ge_i32_e64 s[94:95], v253, 18
	v_cndmask_b32_e64 v121, v236, v121, s[98:99]
	v_cmp_ge_i32_e64 s[96:97], v253, 50
	v_cndmask_b32_e64 v105, v236, v105, s[100:101]
	v_cmp_ge_i32_e64 s[98:99], v253, 19
	v_cndmask_b32_e64 v122, v236, v122, s[94:95]
	v_cmp_ge_i32_e64 s[100:101], v253, 51
	v_cndmask_b32_e64 v106, v236, v106, s[96:97]
	v_cmp_ge_i32_e64 s[94:95], v253, 24
	v_cndmask_b32_e64 v123, v236, v123, s[98:99]
	v_cmp_ge_i32_e64 s[96:97], v253, 56
	v_cndmask_b32_e64 v107, v236, v107, s[100:101]
	v_cmp_ge_i32_e64 s[98:99], v253, 25
	v_cndmask_b32_e64 v124, v236, v124, s[94:95]
	v_cmp_ge_i32_e64 s[100:101], v253, 57
	v_cndmask_b32_e64 v108, v236, v108, s[96:97]
	v_cmp_ge_i32_e64 s[94:95], v253, 26
	v_cndmask_b32_e64 v125, v236, v125, s[98:99]
	v_cmp_ge_i32_e64 s[96:97], v253, 58
	v_cndmask_b32_e64 v109, v236, v109, s[100:101]
	v_cmp_ge_i32_e64 s[98:99], v253, 27
	v_cndmask_b32_e64 v126, v236, v126, s[94:95]
	v_cmp_ge_i32_e64 s[100:101], v253, 59
	v_cndmask_b32_e64 v110, v236, v110, s[96:97]
	v_cndmask_b32_e64 v127, v236, v127, s[98:99]
	v_cndmask_b32_e64 v111, v236, v111, s[100:101]
